# P4 prompt attention: XCD-aware item order (each XCD walks two whole batches; its 32 workgroups share one K/V head at a time under round-robin placement); uses s98-s100
# baseline (speedup 1.0000x reference)
; #define LAS __attribute__((address_space(3)))
; __device__ __forceinline__ void phase_attention(KParams P, LAS unsigned char* lds, const int wave_sg) {
;     ...
;     const int half = wave >> 2, w = wave & 3, r32 = lane & 31, hi = lane >> 5, htid = tid & 255;
;     LAS unsigned char* Kl = lds + half * ATT_HALF; LAS unsigned char* Vl = Kl + 256 * ATT_KROW;
;     u32x4 kreg[8], vreg[8]; bf16x8 qn[4];
;     ...
;     if ((int)blockIdx.x < 2560) ATT_LOAD((int)blockIdx.x);
;     for (int pair = blockIdx.x; pair < 2560; pair += gridDim.x) {
.LBB0_807:
	s_cmpk_lt_i32 s2, 0xa00
	s_cbranch_scc0 .LBB0_830
	v_readlane_b32 s100, v255, 2
	v_readlane_b32 s101, v255, 3
	s_nop 0
	s_load_dwordx2 s[100:101], s[100:101], 0xd0
	s_waitcnt lgkmcnt(0)
	s_cmpk_eq_i32 s100, 0x100
	s_cbranch_scc0 .Lxcdmap_no
	s_and_b32 s98, s2, 7
	s_mul_i32 s98, s98, 0x140
	s_add_i32 s99, s98, 0x13f
	s_lshr_b32 s100, s2, 3
	s_add_i32 s98, s98, s100
	s_mov_b32 s100, 32
	s_branch .Lxcdmap_done
.Lxcdmap_no:
	s_mov_b32 s98, s2
	s_movk_i32 s99, 0x9ff
.Lxcdmap_done:
	s_lshr_b32 s3, s97, 8
	s_bfe_u32 s79, s97, 0x20006
	s_add_u32 s0, s4, 0x1e900000
	s_addc_u32 s1, s5, 0
	s_add_u32 s14, s4, 0x23900000
	s_addc_u32 s15, s5, 0
	s_add_u32 s16, s4, 0x27100000
	s_addc_u32 s17, s5, 0
	s_mul_i32 s4, s3, 0x12000
	s_lshl_b32 s33, s98, 1
	s_add_i32 s12, s4, 0
	s_add_i32 s4, s3, s33
	s_mul_hi_i32 s6, s4, 0x66666667
	s_lshr_b32 s7, s6, 31
	s_ashr_i32 s6, s6, 7
	s_add_i32 s10, s6, s7
	s_mul_i32 s6, s10, 0xfffffec0
	s_add_i32 s6, s6, s4
	s_ashr_i32 s11, s6, 4
	s_ashr_i32 s6, s6, 6
	s_add_i32 s7, s11, -6
	s_cmp_lt_i32 s11, 8
	s_cselect_b32 s6, s6, s7
	s_lshl_b32 s4, s4, 7
	s_and_b32 s13, s4, 0x780
	s_mul_i32 s4, s10, 14
	s_add_i32 s6, s6, s4
	s_ashr_i32 s7, s6, 31
	s_lshl_b64 s[8:9], s[6:7], 18
	s_add_u32 s6, s14, s8
	s_mul_i32 s10, s10, 20
	s_addc_u32 s7, s15, s9
	s_add_i32 s10, s11, s10
	s_ashr_i32 s11, s10, 31
	s_lshl_b64 s[10:11], s[10:11], 11
	s_or_b32 s10, s10, s13
	s_lshl_b32 s4, s79, 5
	v_and_b32_e32 v9, 31, v193
	s_or_b32 s10, s10, s4
	v_or_b32_e32 v0, s10, v9
	s_add_i32 s10, s13, 0xffffff80
	v_mov_b32_e32 v1, s11
	s_add_u32 s8, s16, s8
	v_lshrrev_b32_e32 v8, 5, v198
	v_lshlrev_b64 v[0:1], 7, v[0:1]
	s_addc_u32 s9, s17, s9
	v_lshl_add_u64 v[0:1], s[0:1], 0, v[0:1]
	v_lshlrev_b32_e32 v144, 4, v8
	v_mov_b32_e32 v145, 0
	s_cmp_lg_u32 s13, 0
	v_lshl_add_u64 v[0:1], v[0:1], 0, v[144:145]
	v_bfe_u32 v147, v193, 3, 5
	s_cselect_b32 s11, s10, 0
	global_load_dwordx4 v[140:143], v[0:1], off
	global_load_dwordx4 v[136:139], v[0:1], off offset:32
	global_load_dwordx4 v[132:135], v[0:1], off offset:64
	global_load_dwordx4 v[128:131], v[0:1], off offset:96
	v_lshlrev_b32_e32 v0, 3, v193
	v_or_b32_e32 v2, s11, v147
	v_and_b32_e32 v0, 56, v0
	v_ashrrev_i32_e32 v3, 31, v2
	v_lshlrev_b64 v[4:5], 7, v[2:3]
	v_lshlrev_b32_e32 v1, 1, v0
	v_or_b32_e32 v4, v4, v1
	v_lshl_add_u64 v[6:7], s[6:7], 0, v[4:5]
	v_lshl_add_u64 v[4:5], s[8:9], 0, v[4:5]
	global_load_dwordx4 v[48:51], v[6:7], off
	global_load_dwordx4 v[52:55], v[4:5], off
	v_or_b32_e32 v4, 32, v2
	v_ashrrev_i32_e32 v5, 31, v4
	v_lshlrev_b64 v[4:5], 7, v[4:5]
	v_or_b32_e32 v4, v4, v1
	v_lshl_add_u64 v[6:7], s[6:7], 0, v[4:5]
	v_lshl_add_u64 v[4:5], s[8:9], 0, v[4:5]
	global_load_dwordx4 v[56:59], v[6:7], off
	global_load_dwordx4 v[60:63], v[4:5], off
	v_or_b32_e32 v4, 64, v2
	v_ashrrev_i32_e32 v5, 31, v4
	v_or_b32_e32 v2, 0x60, v2
	v_lshlrev_b64 v[4:5], 7, v[4:5]
	v_ashrrev_i32_e32 v3, 31, v2
	v_or_b32_e32 v4, v4, v1
	v_lshlrev_b64 v[2:3], 7, v[2:3]
	v_lshl_add_u64 v[6:7], s[6:7], 0, v[4:5]
	v_lshl_add_u64 v[4:5], s[8:9], 0, v[4:5]
	v_or_b32_e32 v2, v2, v1
	global_load_dwordx4 v[64:67], v[6:7], off
	global_load_dwordx4 v[68:71], v[4:5], off
	v_lshl_add_u64 v[4:5], s[6:7], 0, v[2:3]
	v_lshl_add_u64 v[2:3], s[8:9], 0, v[2:3]
	global_load_dwordx4 v[72:75], v[4:5], off
	global_load_dwordx4 v[76:79], v[2:3], off
	v_or_b32_e32 v2, 0x80, v147
	v_add_u32_e32 v2, s10, v2
	v_mov_b32_e32 v3, v145
	v_lshlrev_b64 v[2:3], 7, v[2:3]
	v_or_b32_e32 v2, v2, v1
	v_lshl_add_u64 v[4:5], s[6:7], 0, v[2:3]
	v_lshl_add_u64 v[2:3], s[8:9], 0, v[2:3]
	global_load_dwordx4 v[80:83], v[4:5], off
	global_load_dwordx4 v[84:87], v[2:3], off
	v_or_b32_e32 v2, 0xa0, v147
	v_add_u32_e32 v2, s10, v2
	v_mov_b32_e32 v3, v145
	v_lshlrev_b64 v[2:3], 7, v[2:3]
	v_or_b32_e32 v2, v2, v1
	v_lshl_add_u64 v[4:5], s[6:7], 0, v[2:3]
	v_lshl_add_u64 v[2:3], s[8:9], 0, v[2:3]
	v_or_b32_e32 v152, 0xc0, v147
	global_load_dwordx4 v[88:91], v[4:5], off
	global_load_dwordx4 v[92:95], v[2:3], off
	v_add_u32_e32 v2, s10, v152
	v_mov_b32_e32 v3, v145
	v_lshlrev_b64 v[2:3], 7, v[2:3]
	v_or_b32_e32 v2, v2, v1
	v_lshl_add_u64 v[4:5], s[6:7], 0, v[2:3]
	v_lshl_add_u64 v[2:3], s[8:9], 0, v[2:3]
	v_or_b32_e32 v153, 0xe0, v147
	global_load_dwordx4 v[96:99], v[4:5], off
	global_load_dwordx4 v[100:103], v[2:3], off
	v_add_u32_e32 v2, s10, v153
	v_mov_b32_e32 v3, v145
	v_lshlrev_b64 v[2:3], 7, v[2:3]
	v_or_b32_e32 v2, v2, v1
	v_lshl_add_u64 v[4:5], s[6:7], 0, v[2:3]
	v_lshl_add_u64 v[2:3], s[8:9], 0, v[2:3]
	global_load_dwordx4 v[104:107], v[4:5], off
	global_load_dwordx4 v[108:111], v[2:3], off
	v_lshlrev_b32_e32 v2, 2, v8
	v_or_b32_e32 v27, 32, v9
	v_or_b32_e32 v28, 64, v9
	v_sub_u32_e32 v11, v9, v2
	v_sub_u32_e32 v27, v27, v2
	v_sub_u32_e32 v28, v28, v2
	v_cvt_f32_ubyte0_e32 v171, v27
	v_add_u32_e32 v27, 31, v11
	v_cvt_f32_ubyte0_e32 v187, v28
	v_add_u32_e32 v28, 63, v11
	v_cvt_f32_u32_e32 v172, v27
	v_add_u32_e32 v27, 30, v11
	v_cvt_f32_u32_e32 v188, v28
	v_add_u32_e32 v28, 62, v11
	v_cvt_f32_u32_e32 v173, v27
	v_add_u32_e32 v27, 29, v11
	v_cvt_f32_u32_e32 v189, v28
	v_add_u32_e32 v28, 61, v11
	v_cvt_f32_u32_e32 v174, v27
	v_add_u32_e32 v27, 24, v11
	v_cvt_f32_u32_e32 v190, v28
	v_add_u32_e32 v28, 56, v11
	v_bfe_u32 v3, v193, 2, 2
	v_mbcnt_hi_u32_b32 v7, -1, v232
	v_cvt_f32_u32_e32 v175, v27
	v_add_u32_e32 v27, 23, v11
	v_cvt_f32_u32_e32 v191, v28
	v_add_u32_e32 v28, 55, v11
	v_lshl_add_u64 v[148:149], s[0:1], 0, v[144:145]
	v_or3_b32 v3, v3, v2, s4
	s_movk_i32 s0, 0x90
	v_mov_b32_e32 v4, s12
	v_and_b32_e32 v10, 64, v7
	v_cvt_f32_u32_e32 v176, v27
	v_add_u32_e32 v27, 22, v11
	v_cvt_f32_u32_e32 v192, v28
	v_add_u32_e32 v28, 54, v11
	v_lshlrev_b32_e32 v1, 4, v193
; #define LAS __attribute__((address_space(3)))
; __device__ __forceinline__ int crow_c(int r) { return (r & 3) + 8 * (r >> 2); }
; __device__ __forceinline__ void phase_attention(KParams P, LAS unsigned char* lds, const int wave_sg) {
;     ...
;         float sink2 = 0.f, mx = -1e30f, lsum = 0.f;
;         if (hq < 8) { sink2 = sinks[hq] * LOG2E; mx = sink2; lsum = hi == 0 ? 1.f : 0.f; }
;         f32x16 o[2];
;         o[0] = (f32x16){0.f, 0.f, 0.f, 0.f, 0.f, 0.f, 0.f, 0.f, 0.f, 0.f, 0.f, 0.f, 0.f, 0.f, 0.f, 0.f}; o[1] = o[0];
;         const LAS unsigned char* vb = Vl + (32 * w + 4 * hi + ((lane & 15) >> 2)) * ATT_KROW + (16 * ((lane >> 4) & 1) + 4 * (lane & 3)) * 2;
; #pragma unroll
;         for (int kbi = 0; kbi < 5; ++kbi) { const int kb = 4 - kbi;
;             f32x16 S = (f32x16){0.f, 0.f, 0.f, 0.f, 0.f, 0.f, 0.f, 0.f, 0.f, 0.f, 0.f, 0.f, 0.f, 0.f, 0.f, 0.f};
;             const LAS unsigned char* kp = Kl + (32 * w + 32 * kb + r32) * ATT_KROW + hi * 16;
; #pragma unroll
;             for (int d0 = 0; d0 < 4; ++d0) { const bf16x8 kf = *(const LAS bf16x8*)(kp + d0 * 32); S = __builtin_amdgcn_mfma_f32_32x32x16_bf16(kf, qf[d0], S, 0, 0, 0); }
;             float tmax = -1e30f;
; #pragma unroll
;             for (int r = 0; r < 16; ++r) { const int c = crow_c(r) + 4 * hi; const int dist = r32 + 128 - 32 * kb - c;
;                 float v = S[r] - sd * (float)dist;
;                 if (kb == 0) v = dist <= 128 ? v : -1e30f;
;                 if (kb == 4) v = dist >= 0 ? v : -1e30f;
;                 if (kb < 4) { const int ki = 32 * w + 32 * kb + c; v = (hasprev || ki >= 128) ? v : -1e30f; }
;                 S[r] = v; tmax = fmaxf(tmax, v); }
	v_mad_u32_u24 v3, v3, s0, v4
	v_and_b32_e32 v4, 16, v193
	v_xor_b32_e32 v8, 32, v7
	v_add_u32_e32 v10, 64, v10
	v_cvt_f32_u32_e32 v177, v27
	v_add_u32_e32 v27, 21, v11
	v_cvt_f32_u32_e32 v193, v28
	v_add_u32_e32 v28, 53, v11
	v_writelane_b32 v255, s14, 34
	v_cmp_lt_i32_e32 vcc, v8, v10
	v_cvt_f32_u32_e32 v178, v27
	v_add_u32_e32 v27, 16, v11
	v_cvt_f32_u32_e32 v194, v28
	v_add_u32_e32 v28, 48, v11
	v_writelane_b32 v255, s15, 35
	v_cndmask_b32_e32 v7, v7, v8, vcc
	v_mov_b32_e32 v8, 0x1200
	v_cvt_f32_u32_e32 v179, v27
	v_add_u32_e32 v27, 15, v11
	v_cvt_f32_u32_e32 v195, v28
	v_add_u32_e32 v28, 47, v11
	v_writelane_b32 v255, s16, 36
	v_mad_u32_u24 v8, v147, s0, v8
	v_cmp_lt_i32_e64 s[0:1], -1, v11
	v_cvt_f32_u32_e32 v180, v27
	v_add_u32_e32 v27, 14, v11
	v_cvt_f32_u32_e32 v196, v28
	v_add_u32_e32 v28, 46, v11
	v_or_b32_e32 v6, 0x80, v9
	v_writelane_b32 v255, s0, 28
	v_or_b32_e32 v26, 0x9b, v2
	v_cvt_f32_u32_e32 v181, v27
	v_add_u32_e32 v27, 13, v11
	v_cvt_f32_u32_e32 v197, v28
	v_add_u32_e32 v28, 45, v11
	v_cmp_gt_u32_e64 s[8:9], 32, v198
	v_writelane_b32 v255, s1, 29
	v_sub_u32_e32 v26, v6, v26
	s_add_i32 s1, s4, 0x60
	v_cvt_f32_u32_e32 v182, v27
	v_add_u32_e32 v27, 8, v11
	v_cvt_f32_u32_e32 v198, v28
	v_add_u32_e32 v28, 40, v11
	v_and_or_b32 v4, v199, 12, v4
	v_cvt_f32_i32_e32 v170, v26
	v_cmp_lt_i32_e64 s[42:43], -1, v26
	v_or_b32_e32 v26, s1, v9
	v_cvt_f32_u32_e32 v183, v27
	v_add_u32_e32 v27, 7, v11
	s_add_i32 s1, s4, 64
	v_cvt_f32_u32_e32 v199, v28
	v_add_u32_e32 v28, 39, v11
	v_cvt_f32_u32_e32 v184, v27
	v_add_u32_e32 v27, 6, v11
	s_cmp_gt_u32 s79, 1
	v_cvt_f32_u32_e32 v200, v28
	v_add_u32_e32 v28, 38, v11
	v_or_b32_e32 v146, s4, v9
	v_cvt_f32_u32_e32 v185, v27
	v_add_u32_e32 v27, 5, v11
	s_cselect_b64 s[6:7], -1, 0
	v_cvt_f32_u32_e32 v201, v28
	v_add_u32_e32 v28, 37, v11
	s_add_i32 s4, s4, 32
	v_cvt_f32_u32_e32 v186, v27
	v_or_b32_e32 v27, s1, v9
	v_cvt_f32_u32_e32 v202, v28
	v_or_b32_e32 v28, s4, v9
	v_or_b32_e32 v9, 0x60, v9
	v_sub_u32_e32 v9, v9, v2
	v_cvt_f32_ubyte0_e32 v203, v9
	v_add_u32_e32 v9, 0x5f, v11
	v_cvt_f32_u32_e32 v204, v9
	v_add_u32_e32 v9, 0x5e, v11
	v_cvt_f32_u32_e32 v205, v9
	v_add_u32_e32 v9, 0x5d, v11
	v_cvt_f32_u32_e32 v206, v9
	v_add_u32_e32 v9, 0x58, v11
	v_cvt_f32_u32_e32 v207, v9
	v_add_u32_e32 v9, 0x57, v11
	v_cvt_f32_u32_e32 v208, v9
	v_add_u32_e32 v9, 0x56, v11
	v_cvt_f32_u32_e32 v209, v9
	v_add_u32_e32 v9, 0x55, v11
	v_cvt_f32_u32_e32 v210, v9
	v_add_u32_e32 v9, 0x50, v11
	v_cvt_f32_u32_e32 v211, v9
	v_add_u32_e32 v9, 0x4f, v11
	v_cvt_f32_u32_e32 v212, v9
	v_add_u32_e32 v9, 0x4e, v11
	v_cvt_f32_u32_e32 v213, v9
	v_add_u32_e32 v9, 0x4d, v11
	v_cvt_f32_u32_e32 v214, v9
	v_add_u32_e32 v9, 0x48, v11
	v_cvt_f32_u32_e32 v215, v9
	v_add_u32_e32 v9, 0x47, v11
	v_cvt_f32_u32_e32 v216, v9
	v_add_u32_e32 v9, 0x46, v11
	v_or_b32_e32 v12, 0x81, v2
	v_cvt_f32_u32_e32 v217, v9
	v_add_u32_e32 v9, 0x45, v11
	v_and_b32_e32 v1, 0x70, v1
	s_movk_i32 s0, 0x81
	v_sub_u32_e32 v12, v6, v12
	v_or_b32_e32 v13, 0x82, v2
	v_cvt_f32_u32_e32 v218, v9
	v_sub_u32_e32 v9, v6, v2
	v_add_u32_e32 v1, s12, v1
	v_add_u32_e32 v5, s12, v144
	v_cvt_f32_i32_e32 v156, v12
	v_cmp_lt_i32_e64 s[12:13], -1, v12
	v_or_b32_e32 v12, 2, v2
	v_sub_u32_e32 v13, v6, v13
	v_or_b32_e32 v14, 0x83, v2
	v_cvt_f32_ubyte0_e32 v219, v9
	v_cmp_gt_u32_e64 s[44:45], s0, v9
	v_xad_u32 v9, v2, -1, v6
	v_cvt_f32_i32_e32 v157, v13
	v_cmp_lt_i32_e64 s[14:15], -1, v13
	v_or_b32_e32 v13, 3, v2
	v_sub_u32_e32 v14, v6, v14
	v_or_b32_e32 v15, 0x88, v2
	v_cvt_f32_ubyte0_e32 v220, v9
	v_cmp_gt_u32_e64 s[46:47], s0, v9
	v_sub_u32_e32 v9, v6, v12
	s_mov_b32 s89, s17
	v_cvt_f32_i32_e32 v158, v14
	v_cmp_lt_i32_e64 s[16:17], -1, v14
	v_or_b32_e32 v14, 8, v2
	v_sub_u32_e32 v15, v6, v15
	v_or_b32_e32 v16, 0x89, v2
	v_cvt_f32_ubyte0_e32 v221, v9
	v_cmp_gt_u32_e64 s[48:49], s0, v9
	v_sub_u32_e32 v9, v6, v13
	v_cvt_f32_i32_e32 v159, v15
	v_cmp_lt_i32_e64 s[18:19], -1, v15
	v_or_b32_e32 v15, 9, v2
	v_sub_u32_e32 v16, v6, v16
	v_or_b32_e32 v17, 0x8a, v2
	v_cvt_f32_ubyte0_e32 v222, v9
	v_cmp_gt_u32_e64 s[50:51], s0, v9
	v_sub_u32_e32 v9, v6, v14
	v_cvt_f32_i32_e32 v160, v16
	v_cmp_lt_i32_e64 s[20:21], -1, v16
	v_or_b32_e32 v16, 10, v2
	v_sub_u32_e32 v17, v6, v17
	v_or_b32_e32 v18, 0x8b, v2
	v_cvt_f32_ubyte0_e32 v223, v9
	v_cmp_gt_u32_e64 s[52:53], s0, v9
	v_sub_u32_e32 v9, v6, v15
	v_cvt_f32_i32_e32 v161, v17
	v_cmp_lt_i32_e64 s[22:23], -1, v17
	v_or_b32_e32 v17, 11, v2
	v_sub_u32_e32 v18, v6, v18
	v_or_b32_e32 v19, 0x90, v2
	v_cvt_f32_ubyte0_e32 v224, v9
	v_cmp_gt_u32_e64 s[54:55], s0, v9
	v_sub_u32_e32 v9, v6, v16
	v_cvt_f32_i32_e32 v162, v18
	v_cmp_lt_i32_e64 s[24:25], -1, v18
	v_or_b32_e32 v18, 16, v2
	v_sub_u32_e32 v19, v6, v19
	v_or_b32_e32 v20, 0x91, v2
	v_cvt_f32_ubyte0_e32 v225, v9
	v_cmp_gt_u32_e64 s[56:57], s0, v9
	v_sub_u32_e32 v9, v6, v17
	v_cvt_f32_i32_e32 v163, v19
	v_cmp_lt_i32_e64 s[26:27], -1, v19
	v_or_b32_e32 v19, 17, v2
	v_sub_u32_e32 v20, v6, v20
	v_or_b32_e32 v21, 0x92, v2
	v_cvt_f32_ubyte0_e32 v226, v9
	v_cmp_gt_u32_e64 s[58:59], s0, v9
	v_sub_u32_e32 v9, v6, v18
	v_cvt_f32_i32_e32 v164, v20
	v_cmp_lt_i32_e64 s[28:29], -1, v20
	v_or_b32_e32 v20, 18, v2
	v_sub_u32_e32 v21, v6, v21
	v_or_b32_e32 v22, 0x93, v2
	v_cvt_f32_ubyte0_e32 v227, v9
	v_cmp_gt_u32_e64 s[60:61], s0, v9
	v_sub_u32_e32 v9, v6, v19
	v_cvt_f32_i32_e32 v165, v21
	v_cmp_lt_i32_e64 s[30:31], -1, v21
	v_or_b32_e32 v21, 19, v2
	v_sub_u32_e32 v22, v6, v22
	v_or_b32_e32 v23, 0x98, v2
	v_cvt_f32_ubyte0_e32 v228, v9
	v_cmp_gt_u32_e64 s[62:63], s0, v9
	v_sub_u32_e32 v9, v6, v20
	v_cvt_f32_i32_e32 v166, v22
	v_cmp_lt_i32_e64 s[34:35], -1, v22
	v_or_b32_e32 v22, 24, v2
	v_sub_u32_e32 v23, v6, v23
	v_or_b32_e32 v24, 0x99, v2
	v_or_b32_e32 v25, 0x9a, v2
	v_cvt_f32_ubyte0_e32 v229, v9
	v_cmp_gt_u32_e64 s[64:65], s0, v9
	v_sub_u32_e32 v9, v6, v21
	v_cvt_f32_i32_e32 v167, v23
	v_cmp_lt_i32_e64 s[36:37], -1, v23
	v_or_b32_e32 v23, 25, v2
	v_sub_u32_e32 v24, v6, v24
	v_sub_u32_e32 v25, v6, v25
	v_cvt_f32_ubyte0_e32 v230, v9
	v_cmp_gt_u32_e64 s[66:67], s0, v9
	v_sub_u32_e32 v9, v6, v22
	v_cvt_f32_i32_e32 v168, v24
	v_cmp_lt_i32_e64 s[38:39], -1, v24
	v_or_b32_e32 v24, 26, v2
	v_cvt_f32_i32_e32 v169, v25
	v_cmp_lt_i32_e64 s[40:41], -1, v25
	v_or_b32_e32 v25, 27, v2
	v_cvt_f32_ubyte0_e32 v231, v9
	v_cmp_gt_u32_e64 s[68:69], s0, v9
	v_sub_u32_e32 v9, v6, v23
	v_readlane_b32 s10, v255, 2
	v_cvt_f32_ubyte0_e32 v233, v9
	v_cmp_gt_u32_e64 s[70:71], s0, v9
	v_sub_u32_e32 v9, v6, v24
	v_sub_u32_e32 v6, v6, v25
	v_readlane_b32 s11, v255, 3
	v_cmp_gt_u32_e64 s[72:73], s0, v9
	v_cmp_gt_u32_e64 s[74:75], s0, v6
	s_load_dwordx2 s[0:1], s[10:11], 0xd0
	v_cvt_f32_i32_e32 v155, v11
	s_cmp_eq_u32 s79, 3
	s_cselect_b64 s[90:91], -1, 0
	v_lshlrev_b32_e32 v4, 1, v4
	s_waitcnt lgkmcnt(0)
; #define LAS __attribute__((address_space(3)))
; __device__ __forceinline__ void phase_attention(KParams P, LAS unsigned char* lds, const int wave_sg) {
;     ...
;     for (int pair = blockIdx.x; pair < 2560; pair += gridDim.x) {
;         ATT_DECODE(pair);
;         const int nblk = 16 >> (2 * g), blk = j & (nblk - 1), rres = j >> (4 - 2 * g); const bool hasprev = blk != 0;
;         const float sd = exp2f(-0.4f * (float)(hq + 1)) * LOG2E * (float)dil;
;         __syncthreads();
; #pragma unroll
;         for (int c = 0; c < 8; ++c) { const int ch = htid + 256 * c, row = ch >> 3, cc = ch & 7; *(LAS u32x4*)(Kl + row * ATT_KROW + cc * 16) = kreg[c]; *(LAS u32x4*)(Vl + row * ATT_KROW + cc * 16) = vreg[c]; }
;         bf16x8 qf[4];
; #pragma unroll
;         for (int d0 = 0; d0 < 4; ++d0) qf[d0] = qn[d0];
;         __syncthreads();
;         if (pair + (int)gridDim.x < 2560) ATT_LOAD(pair + (int)gridDim.x);
	s_mov_b64 s[76:77], s[0:1]
	s_mov_b32 s76, s100
	s_add_i32 s0, s76, s98
	v_lshlrev_b32_e32 v154, 2, v7
	v_mul_u32_u24_e32 v7, 0x90, v147
	v_mul_u32_u24_e32 v10, 0x90, v146
	v_mul_u32_u24_e32 v26, 0x90, v26
	v_mul_u32_u24_e32 v27, 0x90, v27
	v_mul_u32_u24_e32 v28, 0x90, v28
	s_lshl_b32 s1, s0, 8
	s_lshl_b32 s4, s3, 7
	s_lshl_b32 s0, s0, 1
	s_waitcnt vmcnt(16)
	v_mov_b64_e32 v[112:113], v[128:129]
	v_mov_b64_e32 v[116:117], v[132:133]
	v_mov_b64_e32 v[120:121], v[136:137]
	v_mov_b64_e32 v[124:125], v[140:141]
	s_mov_b32 s5, 0
	v_cvt_f32_ubyte0_e32 v234, v9
	v_cvt_f32_ubyte0_e32 v235, v6
	s_add_i32 s78, s1, s4
	s_lshl_b32 s96, s76, 8
	v_writelane_b32 v255, s0, 37
	s_lshl_b32 s97, s76, 1
	v_add_u32_e32 v236, v1, v7
	v_add_u32_e32 v237, v1, v8
	v_lshlrev_b32_e32 v238, 1, v0
	s_mov_b32 s86, 0xf149f2ca
	v_add_u32_e32 v239, v5, v26
	v_add_u32_e32 v240, v5, v27
	v_add_u32_e32 v241, v5, v28
	v_lshlrev_b32_e32 v144, 1, v2
	v_add_u32_e32 v242, v5, v10
	v_mov_b32_e32 v243, 0xf149f2ca
	v_add_u32_e32 v244, v3, v4
	v_mov_b32_e32 v245, 0x8100
	s_mov_b32 s87, s98
	v_mov_b64_e32 v[114:115], v[130:131]
	v_mov_b64_e32 v[118:119], v[134:135]
	v_mov_b64_e32 v[122:123], v[138:139]
	v_mov_b64_e32 v[126:127], v[142:143]
	s_branch .LBB0_810

; #define LAS __attribute__((address_space(3)))
; __device__ __forceinline__ void phase_attention(KParams P, LAS unsigned char* lds, const int wave_sg) {
;     ...
;     for (int pair = blockIdx.x; pair < 2560; pair += gridDim.x) {
;         ATT_DECODE(pair);
;         const int nblk = 16 >> (2 * g), blk = j & (nblk - 1), rres = j >> (4 - 2 * g); const bool hasprev = blk != 0;
;         const float sd = exp2f(-0.4f * (float)(hq + 1)) * LOG2E * (float)dil;
;         __syncthreads();
; #pragma unroll
;         for (int c = 0; c < 8; ++c) { const int ch = htid + 256 * c, row = ch >> 3, cc = ch & 7; *(LAS u32x4*)(Kl + row * ATT_KROW + cc * 16) = kreg[c]; *(LAS u32x4*)(Vl + row * ATT_KROW + cc * 16) = vreg[c]; }
;         bf16x8 qf[4];
; #pragma unroll
;         for (int d0 = 0; d0 < 4; ++d0) qf[d0] = qn[d0];
;         __syncthreads();
;         if (pair + (int)gridDim.x < 2560) ATT_LOAD(pair + (int)gridDim.x);
.LBB0_810:
	s_add_i32 s4, s33, s3
	s_mul_hi_i32 s0, s4, 0x66666667
	s_lshr_b32 s1, s0, 31
	s_ashr_i32 s0, s0, 7
	s_add_i32 s80, s0, s1
	s_mul_i32 s0, s80, 0xfffffec0
	s_add_i32 s0, s4, s0
	s_ashr_i32 s82, s0, 4
	s_add_i32 s0, s82, 1
	v_cvt_f32_i32_e32 v0, s0
	s_mov_b32 s0, 0xc2fc0000
	v_readlane_b32 s10, v255, 2
	v_readlane_b32 s11, v255, 3
	v_mul_f32_e32 v1, 0xbecccccd, v0
	v_cmp_gt_f32_e64 s[76:77], s0, v1
	s_and_b64 s[0:1], s[76:77], exec
	s_barrier
	s_waitcnt vmcnt(15)
	ds_write_b128 v236, v[48:51]
	s_waitcnt vmcnt(14)
	ds_write_b128 v236, v[52:55] offset:36864
	s_waitcnt vmcnt(13)
	ds_write_b128 v236, v[56:59] offset:4608
	s_waitcnt vmcnt(12)
	ds_write_b128 v236, v[60:63] offset:41472
	s_waitcnt vmcnt(11)
	ds_write_b128 v236, v[64:67] offset:9216
	s_waitcnt vmcnt(10)
	ds_write_b128 v236, v[68:71] offset:46080
	s_waitcnt vmcnt(9)
	ds_write_b128 v236, v[72:75] offset:13824
	s_waitcnt vmcnt(8)
	ds_write_b128 v236, v[76:79] offset:50688
	s_waitcnt vmcnt(7)
	ds_write_b128 v236, v[80:83] offset:18432
	s_waitcnt vmcnt(6)
	ds_write_b128 v236, v[84:87] offset:55296
	s_waitcnt vmcnt(5)
	ds_write_b128 v236, v[88:91] offset:23040
	s_waitcnt vmcnt(4)
	ds_write_b128 v236, v[92:95] offset:59904
	s_waitcnt vmcnt(3)
	ds_write_b128 v236, v[96:99] offset:27648
	s_waitcnt vmcnt(2)
	ds_write_b128 v236, v[100:103] offset:64512
	s_waitcnt vmcnt(1)
	ds_write_b128 v236, v[104:107] offset:32256
	s_waitcnt vmcnt(0)
	ds_write_b128 v237, v[108:111] offset:64512
	s_waitcnt lgkmcnt(0)
	s_barrier
	s_load_dwordx2 s[0:1], s[10:11], 0xd0
	s_cselect_b32 s81, 0xffffffc0, 0
	s_waitcnt lgkmcnt(0)
	s_add_i32 s87, s87, s100
	s_cmp_gt_i32 s87, s99
	s_cselect_b64 s[84:85], -1, 0
	s_and_b64 vcc, exec, s[84:85]
	s_cbranch_vccnz .LBB0_812
	v_readlane_b32 s0, v255, 37
	s_add_i32 s0, s0, s3
	s_mul_hi_i32 s1, s0, 0x66666667
	s_lshr_b32 s83, s1, 31
	s_ashr_i32 s1, s1, 7
	s_add_i32 s83, s1, s83
	s_mul_i32 s1, s83, 0xfffffec0
	s_add_i32 s0, s0, s1
	s_ashr_i32 vcc_lo, s0, 4
	s_ashr_i32 s0, s0, 6
	s_add_i32 s1, vcc_lo, -6
	s_cmp_lt_i32 vcc_lo, 8
	s_cselect_b32 s0, s0, s1
	s_mul_i32 s1, s83, 14
	s_add_i32 s0, s0, s1
	s_ashr_i32 s1, s0, 31
	s_and_b32 s88, s78, 0x780
	s_lshl_b64 s[94:95], s[0:1], 18
	v_readlane_b32 s0, v255, 34
	s_add_u32 s0, s0, s94
	v_readlane_b32 s1, v255, 35
	s_mul_i32 s83, s83, 20
	s_addc_u32 s1, s1, s95
	s_add_i32 vcc_lo, vcc_lo, s83
	s_ashr_i32 vcc_hi, vcc_lo, 31
	s_lshl_b64 vcc, vcc, 11
	s_or_b32 s83, vcc_lo, s88
	v_or_b32_e32 v2, s83, v146
	s_add_i32 s83, s88, 0xffffff80
	v_readlane_b32 s10, v255, 36
	s_add_u32 vcc_lo, s10, s94
	v_mov_b32_e32 v3, vcc_hi
	s_addc_u32 vcc_hi, s89, s95
	v_lshlrev_b64 v[2:3], 7, v[2:3]
	s_cmp_lg_u32 s88, 0
	v_lshl_add_u64 v[2:3], v[148:149], 0, v[2:3]
	s_cselect_b32 s88, s83, 0
	global_load_dwordx4 v[124:127], v[2:3], off
	global_load_dwordx4 v[120:123], v[2:3], off offset:32
	global_load_dwordx4 v[116:119], v[2:3], off offset:64
	global_load_dwordx4 v[112:115], v[2:3], off offset:96
	v_or_b32_e32 v2, s88, v147
	v_ashrrev_i32_e32 v3, 31, v2
	v_lshlrev_b64 v[2:3], 7, v[2:3]
	v_or_b32_e32 v2, v2, v238
	v_lshl_add_u64 v[4:5], s[0:1], 0, v[2:3]
	v_lshl_add_u64 v[2:3], vcc, 0, v[2:3]
	v_or_b32_e32 v1, 32, v147
	global_load_dwordx4 v[48:51], v[4:5], off
	global_load_dwordx4 v[52:55], v[2:3], off
	v_or_b32_e32 v2, s88, v1
	v_ashrrev_i32_e32 v3, 31, v2
	v_lshlrev_b64 v[2:3], 7, v[2:3]
	v_or_b32_e32 v2, v2, v238
	v_lshl_add_u64 v[4:5], s[0:1], 0, v[2:3]
	v_lshl_add_u64 v[2:3], vcc, 0, v[2:3]
	v_or_b32_e32 v1, 64, v147
	global_load_dwordx4 v[56:59], v[4:5], off
	global_load_dwordx4 v[60:63], v[2:3], off
	v_or_b32_e32 v2, s88, v1
	v_ashrrev_i32_e32 v3, 31, v2
	v_lshlrev_b64 v[2:3], 7, v[2:3]
	v_or_b32_e32 v2, v2, v238
	v_lshl_add_u64 v[4:5], s[0:1], 0, v[2:3]
	v_lshl_add_u64 v[2:3], vcc, 0, v[2:3]
	v_or_b32_e32 v1, 0x60, v147
	global_load_dwordx4 v[64:67], v[4:5], off
	global_load_dwordx4 v[68:71], v[2:3], off
	v_or_b32_e32 v2, s88, v1
	v_ashrrev_i32_e32 v3, 31, v2
	v_lshlrev_b64 v[2:3], 7, v[2:3]
	v_or_b32_e32 v2, v2, v238
	v_lshl_add_u64 v[4:5], s[0:1], 0, v[2:3]
	v_lshl_add_u64 v[2:3], vcc, 0, v[2:3]
	v_or_b32_e32 v1, 0x80, v147
	global_load_dwordx4 v[72:75], v[4:5], off
	global_load_dwordx4 v[76:79], v[2:3], off
	v_add_u32_e32 v2, s83, v1
	v_mov_b32_e32 v3, v145
	v_lshlrev_b64 v[2:3], 7, v[2:3]
	v_or_b32_e32 v2, v2, v238
	v_lshl_add_u64 v[4:5], s[0:1], 0, v[2:3]
	v_lshl_add_u64 v[2:3], vcc, 0, v[2:3]
	v_or_b32_e32 v1, 0xa0, v147
	global_load_dwordx4 v[80:83], v[4:5], off
	global_load_dwordx4 v[84:87], v[2:3], off
	v_add_u32_e32 v2, s83, v1
	v_mov_b32_e32 v3, v145
	v_lshlrev_b64 v[2:3], 7, v[2:3]
	v_or_b32_e32 v2, v2, v238
	v_lshl_add_u64 v[4:5], s[0:1], 0, v[2:3]
	v_lshl_add_u64 v[2:3], vcc, 0, v[2:3]
	global_load_dwordx4 v[88:91], v[4:5], off
	global_load_dwordx4 v[92:95], v[2:3], off
	v_add_u32_e32 v2, s83, v152
	v_mov_b32_e32 v3, v145
	v_lshlrev_b64 v[2:3], 7, v[2:3]
	v_or_b32_e32 v2, v2, v238
	v_lshl_add_u64 v[4:5], s[0:1], 0, v[2:3]
	v_lshl_add_u64 v[2:3], vcc, 0, v[2:3]
	global_load_dwordx4 v[96:99], v[4:5], off
	global_load_dwordx4 v[100:103], v[2:3], off
	v_add_u32_e32 v2, s83, v153
	v_mov_b32_e32 v3, v145
	v_lshlrev_b64 v[2:3], 7, v[2:3]
	v_or_b32_e32 v2, v2, v238
	v_lshl_add_u64 v[4:5], s[0:1], 0, v[2:3]
	v_lshl_add_u64 v[2:3], vcc, 0, v[2:3]
	global_load_dwordx4 v[104:107], v[4:5], off
	global_load_dwordx4 v[108:111], v[2:3], off

; #define LAS __attribute__((address_space(3)))
; __global__ void __launch_bounds__(512, 2) mega_fwd(Params Parg) {
;     extern __shared__ __attribute__((aligned(16))) unsigned char lds_raw[];
;     LAS unsigned char* lds = (LAS unsigned char*)lds_raw;
;     cg::grid_group grid = cg::this_grid();
;     const KParams kp0 = (KParams)__builtin_amdgcn_kernarg_segment_ptr();
;     const int wave_sg = __builtin_amdgcn_readfirstlane(threadIdx.x >> 6);
	.amdhsa_kernel _Z8mega_fwd6Params
		.amdhsa_group_segment_fixed_size 0
		.amdhsa_private_segment_fixed_size 0
		.amdhsa_kernarg_size 464
		.amdhsa_user_sgpr_count 2
		.amdhsa_user_sgpr_dispatch_ptr 0
		.amdhsa_user_sgpr_queue_ptr 0
		.amdhsa_user_sgpr_kernarg_segment_ptr 1
		.amdhsa_user_sgpr_dispatch_id 0
		.amdhsa_user_sgpr_kernarg_preload_length 0
		.amdhsa_user_sgpr_kernarg_preload_offset 0
		.amdhsa_user_sgpr_private_segment_size 0
		.amdhsa_uses_dynamic_stack 0
		.amdhsa_enable_private_segment 0
		.amdhsa_system_sgpr_workgroup_id_x 1
		.amdhsa_system_sgpr_workgroup_id_y 0
		.amdhsa_system_sgpr_workgroup_id_z 0
		.amdhsa_system_sgpr_workgroup_info 0
		.amdhsa_system_vgpr_workitem_id 2
		.amdhsa_next_free_vgpr 256
		.amdhsa_next_free_sgpr 102
		.amdhsa_accum_offset 256
		.amdhsa_reserve_vcc 1
		.amdhsa_float_round_mode_32 0
		.amdhsa_float_round_mode_16_64 0
		.amdhsa_float_denorm_mode_32 3
		.amdhsa_float_denorm_mode_16_64 3
		.amdhsa_dx10_clamp 1
		.amdhsa_ieee_mode 1
		.amdhsa_fp16_overflow 0
		.amdhsa_tg_split 0
		.amdhsa_exception_fp_ieee_invalid_op 0
		.amdhsa_exception_fp_denorm_src 0
		.amdhsa_exception_fp_ieee_div_zero 0
		.amdhsa_exception_fp_ieee_overflow 0
		.amdhsa_exception_fp_ieee_underflow 0
		.amdhsa_exception_fp_ieee_inexact 0
		.amdhsa_exception_int_div_zero 0
	.end_amdhsa_kernel

amdhsa.kernels:
  - .agpr_count:     0
    .args:
      - .offset:         0
        .size:           208
        .value_kind:     by_value
      - .offset:         208
        .size:           4
        .value_kind:     hidden_block_count_x
      - .offset:         212
        .size:           4
        .value_kind:     hidden_block_count_y
      - .offset:         216
        .size:           4
        .value_kind:     hidden_block_count_z
      - .offset:         220
        .size:           2
        .value_kind:     hidden_group_size_x
      - .offset:         222
        .size:           2
        .value_kind:     hidden_group_size_y
      - .offset:         224
        .size:           2
        .value_kind:     hidden_group_size_z
      - .offset:         226
        .size:           2
        .value_kind:     hidden_remainder_x
      - .offset:         228
        .size:           2
        .value_kind:     hidden_remainder_y
      - .offset:         230
        .size:           2
        .value_kind:     hidden_remainder_z
      - .offset:         248
        .size:           8
        .value_kind:     hidden_global_offset_x
      - .offset:         256
        .size:           8
        .value_kind:     hidden_global_offset_y
      - .offset:         264
        .size:           8
        .value_kind:     hidden_global_offset_z
      - .offset:         272
        .size:           2
        .value_kind:     hidden_grid_dims
      - .offset:         296
        .size:           8
        .value_kind:     hidden_multigrid_sync_arg
      - .offset:         328
        .size:           4
        .value_kind:     hidden_dynamic_lds_size
    .group_segment_fixed_size: 0
    .kernarg_segment_align: 8
    .kernarg_segment_size: 464
    .language:       OpenCL C
    .language_version:
      - 2
      - 0
    .max_flat_workgroup_size: 512
    .name:           _Z8mega_fwd6Params
    .private_segment_fixed_size: 0
    .sgpr_count:     108
    .sgpr_spill_count: 44
    .symbol:         _Z8mega_fwd6Params.kd
    .uniform_work_group_size: 1
    .uses_dynamic_stack: false
    .vgpr_count:     256
    .vgpr_spill_count: 0
    .wavefront_size: 64
